# grid barrier: non-leader workgroups poll the top-level generation word directly (skip the per-XCD release hop); each still does its own agent-scope acquire
# speedup vs baseline: 1.0150x; 1.0027x over previous
; __device__ __forceinline__ unsigned xb_ld(unsigned* p)              { return __hip_atomic_load(p, __ATOMIC_RELAXED, __HIP_MEMORY_SCOPE_AGENT); }
; __device__ __forceinline__ unsigned xb_add(unsigned* p, unsigned v) { return __hip_atomic_fetch_add(p, v, __ATOMIC_RELAXED, __HIP_MEMORY_SCOPE_AGENT); }
; #define XB_SPIN(cond, bar) do { unsigned _sp = 0; while (cond) { __builtin_amdgcn_s_sleep(1); \
;     if ((++_sp & 255u) == 0u) { if (xb_ld(&(bar)[XB_TMO])) break; if (_sp > XB_SPIN_CAP) { atomicAdd(&(bar)[XB_TMO], 1u); break; } } } } while (0)
; __device__ __forceinline__ void xcd_barrier(const XcdBarrier& b) {
;     ...
;         if (nloc == 0u) { xcd_barrier_complete(bar, b.x, nloc, nx); b.st[0] = nloc; b.st[1] = nx; }
;         const unsigned old = xb_add(&bar[XB_XSUB(b.x)], 1u);
;         const unsigned gen = old / nloc;
;         if (old + 1u == (gen + 1u) * nloc) {
;             __builtin_amdgcn_fence(__ATOMIC_RELEASE, "agent");
;             asm volatile("s_waitcnt vmcnt(0)" ::: "memory");
;             const unsigned og = xb_add(&bar[XB_TOP], 1u);
;             const unsigned tg = og / nx;
;             if (og + 1u == (tg + 1u) * nx) xb_add(&bar[XB_TOPGEN], 1u);
;             else XB_SPIN(xb_ld(&bar[XB_TOPGEN]) == tg, bar);
;             __builtin_amdgcn_fence(__ATOMIC_ACQUIRE, "agent");
;             xb_add(&bar[XB_XGEN(b.x)], 1u);
;             asm volatile("s_waitcnt vmcnt(0)" ::: "memory");
;         } else {
;             XB_SPIN(xb_ld(&bar[XB_XGEN(b.x)]) == gen, bar);
;             __builtin_amdgcn_fence(__ATOMIC_ACQUIRE, "agent");
;             asm volatile("s_waitcnt vmcnt(0)" ::: "memory");
;         }
.LBB0_59:
	s_lshl_b32 s0, s33, 8
	s_add_u32 s23, s36, s0
	s_addc_u32 s22, s37, 0
	v_mov_b32_e32 v1, s23
	v_add_co_u32_e32 v4, vcc, 0x1000, v1
	v_mov_b32_e32 v1, s22
	s_nop 0
	v_addc_co_u32_e32 v5, vcc, 0, v1, vcc
	v_mov_b32_e32 v1, 1
	flat_atomic_add v1, v[4:5], v1 offset:1024 sc0
	v_cvt_f32_u32_e32 v3, v2
	v_sub_u32_e32 v4, 0, v2
	v_rcp_iflag_f32_e32 v3, v3
	s_nop 0
	v_mul_f32_e32 v3, 0x4f7ffffe, v3
	v_cvt_u32_f32_e32 v3, v3
	v_mul_lo_u32 v4, v4, v3
	v_mul_hi_u32 v4, v3, v4
	v_add_u32_e32 v3, v3, v4
	s_waitcnt vmcnt(0) lgkmcnt(0)
	v_mul_hi_u32 v3, v1, v3
	v_mul_lo_u32 v5, v3, v2
	v_add_u32_e32 v4, 1, v1
	v_sub_u32_e32 v1, v1, v5
	v_add_u32_e32 v6, 1, v3
	v_cmp_ge_u32_e32 vcc, v1, v2
	v_sub_u32_e32 v5, v1, v2
	s_nop 0
	v_cndmask_b32_e32 v3, v3, v6, vcc
	v_cndmask_b32_e32 v1, v1, v5, vcc
	v_add_u32_e32 v5, 1, v3
	v_cmp_ge_u32_e32 vcc, v1, v2
	s_nop 1
	v_cndmask_b32_e32 v1, v3, v5, vcc
	v_mad_u64_u32 v[2:3], s[0:1], v2, v1, v[2:3]
	v_cmp_ne_u32_e32 vcc, v4, v2
	s_and_saveexec_b64 s[0:1], vcc
	s_xor_b64 s[0:1], exec, s[0:1]
	s_cbranch_execz .LBB0_72
	v_mov_b32_e32 v0, s36
	v_add_co_u32_e32 v2, vcc, 0x3100, v0
	v_mov_b32_e32 v0, s37
	s_nop 0
	v_addc_co_u32_e32 v3, vcc, 0, v0, vcc
	flat_load_dword v0, v[2:3] offset:1024 sc1
	s_add_u32 s6, s36, 0x3500
	s_addc_u32 s7, s37, 0
	s_waitcnt vmcnt(0) lgkmcnt(0)
	v_cmp_eq_u32_e32 vcc, v0, v1
	s_and_saveexec_b64 s[4:5], vcc
	s_cbranch_execz .LBB0_71
	s_mov_b32 s24, 1
	s_mov_b64 s[8:9], 0
	s_branch .LBB0_63

; __device__ __forceinline__ unsigned xb_ld(unsigned* p)              { return __hip_atomic_load(p, __ATOMIC_RELAXED, __HIP_MEMORY_SCOPE_AGENT); }
; __device__ __forceinline__ unsigned xb_add(unsigned* p, unsigned v) { return __hip_atomic_fetch_add(p, v, __ATOMIC_RELAXED, __HIP_MEMORY_SCOPE_AGENT); }
; #define XB_SPIN(cond, bar) do { unsigned _sp = 0; while (cond) { __builtin_amdgcn_s_sleep(1); \
;     if ((++_sp & 255u) == 0u) { if (xb_ld(&(bar)[XB_TMO])) break; if (_sp > XB_SPIN_CAP) { atomicAdd(&(bar)[XB_TMO], 1u); break; } } } } while (0)
; __device__ __forceinline__ void xcd_barrier(const XcdBarrier& b) {
;     ...
;         if (nloc == 0u) { xcd_barrier_complete(bar, b.x, nloc, nx); b.st[0] = nloc; b.st[1] = nx; }
;         const unsigned old = xb_add(&bar[XB_XSUB(b.x)], 1u);
;         const unsigned gen = old / nloc;
;         if (old + 1u == (gen + 1u) * nloc) {
;             __builtin_amdgcn_fence(__ATOMIC_RELEASE, "agent");
;             asm volatile("s_waitcnt vmcnt(0)" ::: "memory");
;             const unsigned og = xb_add(&bar[XB_TOP], 1u);
;             const unsigned tg = og / nx;
;             if (og + 1u == (tg + 1u) * nx) xb_add(&bar[XB_TOPGEN], 1u);
;             else XB_SPIN(xb_ld(&bar[XB_TOPGEN]) == tg, bar);
;             __builtin_amdgcn_fence(__ATOMIC_ACQUIRE, "agent");
;             xb_add(&bar[XB_XGEN(b.x)], 1u);
;             asm volatile("s_waitcnt vmcnt(0)" ::: "memory");
;         } else {
;             XB_SPIN(xb_ld(&bar[XB_XGEN(b.x)]) == gen, bar);
;             __builtin_amdgcn_fence(__ATOMIC_ACQUIRE, "agent");
;             asm volatile("s_waitcnt vmcnt(0)" ::: "memory");
;         }
.LBB0_128:
	v_readlane_b32 s4, v254, 26
	s_lshl_b32 s4, s4, 2
	s_add_u32 s5, s20, s4
	s_addc_u32 s4, s21, 0
	v_mov_b32_e32 v5, s5
	v_add_co_u32_e32 v8, vcc, 0x1000, v5
	v_mov_b32_e32 v5, s4
	s_nop 0
	v_addc_co_u32_e32 v9, vcc, 0, v5, vcc
	flat_atomic_add v5, v[8:9], v252 offset:1024 sc0
	v_cvt_f32_u32_e32 v7, v6
	v_sub_u32_e32 v8, 0, v6
	v_rcp_iflag_f32_e32 v7, v7
	s_nop 0
	v_mul_f32_e32 v7, 0x4f7ffffe, v7
	v_cvt_u32_f32_e32 v7, v7
	v_mul_lo_u32 v8, v8, v7
	v_mul_hi_u32 v8, v7, v8
	v_add_u32_e32 v7, v7, v8
	s_waitcnt vmcnt(0) lgkmcnt(0)
	v_mul_hi_u32 v7, v5, v7
	v_mul_lo_u32 v9, v7, v6
	v_add_u32_e32 v8, 1, v5
	v_sub_u32_e32 v5, v5, v9
	v_add_u32_e32 v10, 1, v7
	v_cmp_ge_u32_e32 vcc, v5, v6
	v_sub_u32_e32 v9, v5, v6
	s_nop 0
	v_cndmask_b32_e32 v7, v7, v10, vcc
	v_cndmask_b32_e32 v5, v5, v9, vcc
	v_add_u32_e32 v9, 1, v7
	v_cmp_ge_u32_e32 vcc, v5, v6
	s_nop 1
	v_cndmask_b32_e32 v5, v7, v9, vcc
	v_mad_u64_u32 v[6:7], s[26:27], v6, v5, v[6:7]
	v_cmp_ne_u32_e32 vcc, v8, v6
	s_and_saveexec_b64 s[26:27], vcc
	s_xor_b64 s[26:27], exec, s[26:27]
	s_cbranch_execz .LBB0_141
	v_mov_b32_e32 v4, s20
	v_add_co_u32_e32 v6, vcc, 0x3100, v4
	v_mov_b32_e32 v4, s21
	s_nop 0
	v_addc_co_u32_e32 v7, vcc, 0, v4, vcc
	flat_load_dword v4, v[6:7] offset:1024 sc1
	s_add_u32 s36, s20, 0x3500
	s_addc_u32 s37, s21, 0
	s_waitcnt vmcnt(0) lgkmcnt(0)
	v_cmp_eq_u32_e32 vcc, v4, v5
	s_and_saveexec_b64 s[30:31], vcc
	s_cbranch_execz .LBB0_140
	s_mov_b32 s16, 1
	s_mov_b64 s[38:39], 0
	s_branch .LBB0_132

; __device__ __forceinline__ unsigned xb_ld(unsigned* p)              { return __hip_atomic_load(p, __ATOMIC_RELAXED, __HIP_MEMORY_SCOPE_AGENT); }
; __device__ __forceinline__ unsigned xb_add(unsigned* p, unsigned v) { return __hip_atomic_fetch_add(p, v, __ATOMIC_RELAXED, __HIP_MEMORY_SCOPE_AGENT); }
; #define XB_SPIN(cond, bar) do { unsigned _sp = 0; while (cond) { __builtin_amdgcn_s_sleep(1); \
;     if ((++_sp & 255u) == 0u) { if (xb_ld(&(bar)[XB_TMO])) break; if (_sp > XB_SPIN_CAP) { atomicAdd(&(bar)[XB_TMO], 1u); break; } } } } while (0)
; __device__ __forceinline__ void xcd_barrier(const XcdBarrier& b) {
;     ...
;         if (nloc == 0u) { xcd_barrier_complete(bar, b.x, nloc, nx); b.st[0] = nloc; b.st[1] = nx; }
;         const unsigned old = xb_add(&bar[XB_XSUB(b.x)], 1u);
;         const unsigned gen = old / nloc;
;         if (old + 1u == (gen + 1u) * nloc) {
;             __builtin_amdgcn_fence(__ATOMIC_RELEASE, "agent");
;             asm volatile("s_waitcnt vmcnt(0)" ::: "memory");
;             const unsigned og = xb_add(&bar[XB_TOP], 1u);
;             const unsigned tg = og / nx;
;             if (og + 1u == (tg + 1u) * nx) xb_add(&bar[XB_TOPGEN], 1u);
;             else XB_SPIN(xb_ld(&bar[XB_TOPGEN]) == tg, bar);
;             __builtin_amdgcn_fence(__ATOMIC_ACQUIRE, "agent");
;             xb_add(&bar[XB_XGEN(b.x)], 1u);
;             asm volatile("s_waitcnt vmcnt(0)" ::: "memory");
;         } else {
;             XB_SPIN(xb_ld(&bar[XB_XGEN(b.x)]) == gen, bar);
;             __builtin_amdgcn_fence(__ATOMIC_ACQUIRE, "agent");
;             asm volatile("s_waitcnt vmcnt(0)" ::: "memory");
;         }
.LBB0_218:
	v_readlane_b32 s4, v254, 26
	s_lshl_b32 s4, s4, 2
	s_add_u32 s5, s26, s4
	s_addc_u32 s4, s27, 0
	v_mov_b32_e32 v5, s5
	v_add_co_u32_e32 v8, vcc, 0x1000, v5
	v_mov_b32_e32 v5, s4
	s_nop 0
	v_addc_co_u32_e32 v9, vcc, 0, v5, vcc
	flat_atomic_add v7, v[8:9], v252 offset:1024 sc0
	v_cvt_f32_u32_e32 v5, v6
	v_sub_u32_e32 v8, 0, v6
	v_rcp_iflag_f32_e32 v5, v5
	s_nop 0
	v_mul_f32_e32 v5, 0x4f7ffffe, v5
	v_cvt_u32_f32_e32 v5, v5
	v_mul_lo_u32 v8, v8, v5
	v_mul_hi_u32 v8, v5, v8
	v_add_u32_e32 v5, v5, v8
	s_waitcnt vmcnt(0) lgkmcnt(0)
	v_mul_hi_u32 v5, v7, v5
	v_mul_lo_u32 v8, v5, v6
	v_sub_u32_e32 v8, v7, v8
	v_cmp_ge_u32_e32 vcc, v8, v6
	v_add_u32_e32 v9, 1, v5
	s_nop 0
	v_cndmask_b32_e32 v5, v5, v9, vcc
	v_sub_u32_e32 v9, v8, v6
	v_cndmask_b32_e32 v8, v8, v9, vcc
	v_cmp_ge_u32_e32 vcc, v8, v6
	v_add_u32_e32 v8, 1, v5
	s_nop 0
	v_cndmask_b32_e32 v5, v5, v8, vcc
	v_add_u32_e32 v8, 1, v7
	v_mad_u64_u32 v[6:7], s[30:31], v6, v5, v[6:7]
	v_cmp_ne_u32_e32 vcc, v8, v6
	s_and_saveexec_b64 s[30:31], vcc
	s_xor_b64 s[30:31], exec, s[30:31]
	s_cbranch_execz .LBB0_231
	v_mov_b32_e32 v4, s26
	v_add_co_u32_e32 v6, vcc, 0x3100, v4
	v_mov_b32_e32 v4, s27
	s_nop 0
	v_addc_co_u32_e32 v7, vcc, 0, v4, vcc
	flat_load_dword v4, v[6:7] offset:1024 sc1
	s_add_u32 s38, s26, 0x3500
	s_addc_u32 s39, s27, 0
	s_waitcnt vmcnt(0) lgkmcnt(0)
	v_cmp_eq_u32_e32 vcc, v4, v5
	s_and_saveexec_b64 s[36:37], vcc
	s_cbranch_execz .LBB0_230
	s_mov_b32 s16, 1
	s_mov_b64 s[40:41], 0
	s_branch .LBB0_222

; __device__ __forceinline__ unsigned xb_ld(unsigned* p)              { return __hip_atomic_load(p, __ATOMIC_RELAXED, __HIP_MEMORY_SCOPE_AGENT); }
; __device__ __forceinline__ unsigned xb_add(unsigned* p, unsigned v) { return __hip_atomic_fetch_add(p, v, __ATOMIC_RELAXED, __HIP_MEMORY_SCOPE_AGENT); }
; #define XB_SPIN(cond, bar) do { unsigned _sp = 0; while (cond) { __builtin_amdgcn_s_sleep(1); \
;     if ((++_sp & 255u) == 0u) { if (xb_ld(&(bar)[XB_TMO])) break; if (_sp > XB_SPIN_CAP) { atomicAdd(&(bar)[XB_TMO], 1u); break; } } } } while (0)
; __device__ __forceinline__ void xcd_barrier(const XcdBarrier& b) {
;     ...
;         if (nloc == 0u) { xcd_barrier_complete(bar, b.x, nloc, nx); b.st[0] = nloc; b.st[1] = nx; }
;         const unsigned old = xb_add(&bar[XB_XSUB(b.x)], 1u);
;         const unsigned gen = old / nloc;
;         if (old + 1u == (gen + 1u) * nloc) {
;             __builtin_amdgcn_fence(__ATOMIC_RELEASE, "agent");
;             asm volatile("s_waitcnt vmcnt(0)" ::: "memory");
;             const unsigned og = xb_add(&bar[XB_TOP], 1u);
;             const unsigned tg = og / nx;
;             if (og + 1u == (tg + 1u) * nx) xb_add(&bar[XB_TOPGEN], 1u);
;             else XB_SPIN(xb_ld(&bar[XB_TOPGEN]) == tg, bar);
;             __builtin_amdgcn_fence(__ATOMIC_ACQUIRE, "agent");
;             xb_add(&bar[XB_XGEN(b.x)], 1u);
;             asm volatile("s_waitcnt vmcnt(0)" ::: "memory");
;         } else {
;             XB_SPIN(xb_ld(&bar[XB_XGEN(b.x)]) == gen, bar);
;             __builtin_amdgcn_fence(__ATOMIC_ACQUIRE, "agent");
;             asm volatile("s_waitcnt vmcnt(0)" ::: "memory");
;         }
.LBB0_540:
	v_readlane_b32 s4, v254, 26
	s_lshl_b32 s4, s4, 2
	s_add_u32 s5, s20, s4
	s_addc_u32 s4, s21, 0
	v_mov_b32_e32 v5, s5
	v_add_co_u32_e32 v8, vcc, 0x1000, v5
	v_mov_b32_e32 v5, s4
	s_nop 0
	v_addc_co_u32_e32 v9, vcc, 0, v5, vcc
	flat_atomic_add v7, v[8:9], v252 offset:1024 sc0
	v_cvt_f32_u32_e32 v5, v6
	v_sub_u32_e32 v8, 0, v6
	v_rcp_iflag_f32_e32 v5, v5
	s_nop 0
	v_mul_f32_e32 v5, 0x4f7ffffe, v5
	v_cvt_u32_f32_e32 v5, v5
	v_mul_lo_u32 v8, v8, v5
	v_mul_hi_u32 v8, v5, v8
	v_add_u32_e32 v5, v5, v8
	s_waitcnt vmcnt(0) lgkmcnt(0)
	v_mul_hi_u32 v5, v7, v5
	v_mul_lo_u32 v8, v5, v6
	v_sub_u32_e32 v8, v7, v8
	v_cmp_ge_u32_e32 vcc, v8, v6
	v_add_u32_e32 v9, 1, v5
	s_nop 0
	v_cndmask_b32_e32 v5, v5, v9, vcc
	v_sub_u32_e32 v9, v8, v6
	v_cndmask_b32_e32 v8, v8, v9, vcc
	v_cmp_ge_u32_e32 vcc, v8, v6
	v_add_u32_e32 v8, 1, v5
	s_nop 0
	v_cndmask_b32_e32 v5, v5, v8, vcc
	v_add_u32_e32 v8, 1, v7
	v_mad_u64_u32 v[6:7], s[30:31], v6, v5, v[6:7]
	v_cmp_ne_u32_e32 vcc, v8, v6
	s_and_saveexec_b64 s[30:31], vcc
	s_xor_b64 s[30:31], exec, s[30:31]
	s_cbranch_execz .LBB0_553
	v_mov_b32_e32 v4, s20
	v_add_co_u32_e32 v6, vcc, 0x3100, v4
	v_mov_b32_e32 v4, s21
	s_nop 0
	v_addc_co_u32_e32 v7, vcc, 0, v4, vcc
	flat_load_dword v4, v[6:7] offset:1024 sc1
	s_add_u32 s38, s20, 0x3500
	s_addc_u32 s39, s21, 0
	s_waitcnt vmcnt(0) lgkmcnt(0)
	v_cmp_eq_u32_e32 vcc, v4, v5
	s_and_saveexec_b64 s[36:37], vcc
	s_cbranch_execz .LBB0_552
	s_mov_b32 s16, 1
	s_mov_b64 s[40:41], 0
	s_branch .LBB0_544

; __device__ __forceinline__ unsigned xb_ld(unsigned* p)              { return __hip_atomic_load(p, __ATOMIC_RELAXED, __HIP_MEMORY_SCOPE_AGENT); }
; __device__ __forceinline__ unsigned xb_add(unsigned* p, unsigned v) { return __hip_atomic_fetch_add(p, v, __ATOMIC_RELAXED, __HIP_MEMORY_SCOPE_AGENT); }
; #define XB_SPIN(cond, bar) do { unsigned _sp = 0; while (cond) { __builtin_amdgcn_s_sleep(1); \
;     if ((++_sp & 255u) == 0u) { if (xb_ld(&(bar)[XB_TMO])) break; if (_sp > XB_SPIN_CAP) { atomicAdd(&(bar)[XB_TMO], 1u); break; } } } } while (0)
; __device__ __forceinline__ void xcd_barrier(const XcdBarrier& b) {
;     ...
;         if (nloc == 0u) { xcd_barrier_complete(bar, b.x, nloc, nx); b.st[0] = nloc; b.st[1] = nx; }
;         const unsigned old = xb_add(&bar[XB_XSUB(b.x)], 1u);
;         const unsigned gen = old / nloc;
;         if (old + 1u == (gen + 1u) * nloc) {
;             __builtin_amdgcn_fence(__ATOMIC_RELEASE, "agent");
;             asm volatile("s_waitcnt vmcnt(0)" ::: "memory");
;             const unsigned og = xb_add(&bar[XB_TOP], 1u);
;             const unsigned tg = og / nx;
;             if (og + 1u == (tg + 1u) * nx) xb_add(&bar[XB_TOPGEN], 1u);
;             else XB_SPIN(xb_ld(&bar[XB_TOPGEN]) == tg, bar);
;             __builtin_amdgcn_fence(__ATOMIC_ACQUIRE, "agent");
;             xb_add(&bar[XB_XGEN(b.x)], 1u);
;             asm volatile("s_waitcnt vmcnt(0)" ::: "memory");
;         } else {
;             XB_SPIN(xb_ld(&bar[XB_XGEN(b.x)]) == gen, bar);
;             __builtin_amdgcn_fence(__ATOMIC_ACQUIRE, "agent");
;             asm volatile("s_waitcnt vmcnt(0)" ::: "memory");
;         }
.LBB0_717:
	v_readlane_b32 s2, v254, 26
	s_lshl_b32 s2, s2, 2
	s_add_u32 s4, s18, s2
	s_addc_u32 s2, s19, 0
	v_mov_b32_e32 v5, s4
	v_add_co_u32_e32 v8, vcc, 0x1000, v5
	v_mov_b32_e32 v5, s2
	s_nop 0
	v_addc_co_u32_e32 v9, vcc, 0, v5, vcc
	flat_atomic_add v7, v[8:9], v252 offset:1024 sc0
	v_cvt_f32_u32_e32 v5, v6
	v_sub_u32_e32 v8, 0, v6
	v_rcp_iflag_f32_e32 v5, v5
	s_nop 0
	v_mul_f32_e32 v5, 0x4f7ffffe, v5
	v_cvt_u32_f32_e32 v5, v5
	v_mul_lo_u32 v8, v8, v5
	v_mul_hi_u32 v8, v5, v8
	v_add_u32_e32 v5, v5, v8
	s_waitcnt vmcnt(0) lgkmcnt(0)
	v_mul_hi_u32 v5, v7, v5
	v_mul_lo_u32 v8, v5, v6
	v_sub_u32_e32 v8, v7, v8
	v_cmp_ge_u32_e32 vcc, v8, v6
	v_add_u32_e32 v9, 1, v5
	s_nop 0
	v_cndmask_b32_e32 v5, v5, v9, vcc
	v_sub_u32_e32 v9, v8, v6
	v_cndmask_b32_e32 v8, v8, v9, vcc
	v_cmp_ge_u32_e32 vcc, v8, v6
	v_add_u32_e32 v8, 1, v5
	s_nop 0
	v_cndmask_b32_e32 v5, v5, v8, vcc
	v_add_u32_e32 v8, 1, v7
	v_mad_u64_u32 v[6:7], s[20:21], v6, v5, v[6:7]
	v_cmp_ne_u32_e32 vcc, v8, v6
	s_and_saveexec_b64 s[20:21], vcc
	s_xor_b64 s[20:21], exec, s[20:21]
	s_cbranch_execz .LBB0_730
	v_mov_b32_e32 v4, s18
	v_add_co_u32_e32 v6, vcc, 0x3100, v4
	v_mov_b32_e32 v4, s19
	s_nop 0
	v_addc_co_u32_e32 v7, vcc, 0, v4, vcc
	flat_load_dword v4, v[6:7] offset:1024 sc1
	s_add_u32 s30, s18, 0x3500
	s_addc_u32 s31, s19, 0
	s_waitcnt vmcnt(0) lgkmcnt(0)
	v_cmp_eq_u32_e32 vcc, v4, v5
	s_and_saveexec_b64 s[26:27], vcc
	s_cbranch_execz .LBB0_729
	s_mov_b32 s5, 1
	s_mov_b64 s[36:37], 0
	s_branch .LBB0_721
